# grid barrier: the top counter is replicated per XCC (each XCD leader bumps all replicas, a workgroup polls its own XCC's replica) so 256 pollers no longer share one memory channel
# speedup vs baseline: 1.0095x; 1.0058x over previous
.LBB0_579:
	v_readlane_b32 s12, v253, 46
	v_readlane_b32 s13, v253, 47
	v_readlane_b32 s14, v253, 48
	v_readlane_b32 s15, v253, 49
	v_readlane_b32 s18, v253, 50
	v_readlane_b32 s19, v253, 51
	v_mov_b32_e32 v1, 0
	v_mov_b32_e32 v6, 1
	s_add_u32 s18, s18, 0xfffff000
	s_addc_u32 s19, s19, -1
	s_waitcnt lgkmcnt(0)
	s_nop 4
	global_atomic_add v6, v1, v6, s[12:13] sc0
	v_cvt_f32_u32_e32 v5, v3
	v_sub_u32_e32 v4, 0, v3
	v_rcp_iflag_f32_e32 v5, v5
	s_nop 1
	v_mul_f32_e32 v5, 0x4f7ffffe, v5
	v_cvt_u32_f32_e32 v5, v5
	v_mul_lo_u32 v0, v4, v5
	v_mul_hi_u32 v0, v5, v0
	v_add_u32_e32 v0, v5, v0
	s_waitcnt vmcnt(0)
	v_mul_hi_u32 v0, v6, v0
	v_mul_lo_u32 v4, v0, v3
	v_sub_u32_e32 v4, v6, v4
	v_add_u32_e32 v5, 1, v0
	v_cmp_ge_u32_e32 vcc, v4, v3
	s_nop 1
	v_cndmask_b32_e32 v0, v0, v5, vcc
	v_sub_u32_e32 v5, v4, v3
	v_cndmask_b32_e32 v4, v4, v5, vcc
	v_add_u32_e32 v5, 1, v0
	v_cmp_ge_u32_e32 vcc, v4, v3
	s_nop 1
	v_cndmask_b32_e32 v0, v0, v5, vcc
	v_add_u32_e32 v0, 1, v0
	v_mul_lo_u32 v4, v0, v3
	v_mul_lo_u32 v5, v0, v2
	v_add_u32_e32 v6, 1, v6
	v_cmp_ne_u32_e32 vcc, v6, v4
	s_mov_b32 s16, 0
	s_cbranch_vccnz .Lxb_wait
	buffer_wbl2 sc1
	s_waitcnt vmcnt(0)
	v_mov_b32_e32 v4, 1
	global_atomic_add v1, v4, s[18:19]
	global_atomic_add v1, v4, s[18:19] offset:256
	global_atomic_add v1, v4, s[18:19] offset:512
	global_atomic_add v1, v4, s[18:19] offset:768
	global_atomic_add v1, v4, s[18:19] offset:1024
	global_atomic_add v1, v4, s[18:19] offset:1280
	global_atomic_add v1, v4, s[18:19] offset:1536
	global_atomic_add v1, v4, s[18:19] offset:1792
	global_atomic_add v1, v4, s[18:19] offset:2048
	global_atomic_add v1, v4, s[18:19] offset:2304
	global_atomic_add v1, v4, s[18:19] offset:2560
	global_atomic_add v1, v4, s[18:19] offset:2816
	global_atomic_add v1, v4, s[18:19] offset:3072
	global_atomic_add v1, v4, s[18:19] offset:3328
	global_atomic_add v1, v4, s[18:19] offset:3584
	global_atomic_add v1, v4, s[18:19] offset:3840
	s_branch .Lxb_poll
